# one-time per-XCD start offset (x * ~3us) after phase 0 so the eight independent sequence pipelines de-synchronise their epilogue bursts
# speedup vs baseline: 1.0078x; 1.0037x over previous
; __device__ __forceinline__ unsigned xb_ld(unsigned* p)              { return __hip_atomic_load(p, __ATOMIC_RELAXED, __HIP_MEMORY_SCOPE_AGENT); }
; __global__ void __launch_bounds__(512, 2) fwd_megakernel(Args a) {
;     ...
;             if (s == 0) {
;                 if (threadIdx.x == 0) { unsigned ok = (G == 256) ? 1u : 0u;
;                     for (unsigned j = 0; j < 16; ++j) { const unsigned c = xb_ld(&bar.bar[XB_XCNT(j)]); ok &= (j < 8) ? (c == 32u) : (c == 0u); }
;                     bst[3] = ok; }
;                 __syncthreads();
;                 grp = __builtin_amdgcn_readfirstlane((int)bst[3]);
;                 if (grp) vb = __builtin_amdgcn_readfirstlane((int)bst[2]) * 8 + (int)bar.x;
.LBB0_27:
	s_or_b64 exec, exec, s[2:3]
	v_readlane_b32 s2, v255, 3
	s_waitcnt vmcnt(0) lgkmcnt(0)
	s_barrier
	v_mov_b32_e32 v0, s2
	ds_read_b32 v0, v0
	s_mov_b32 s3, 0
	v_writelane_b32 v255, s3, 5
	s_waitcnt lgkmcnt(0)
	v_readfirstlane_b32 s2, v0
	s_cmp_eq_u32 s2, 0
	s_cbranch_scc1 .LBB0_11
	v_readlane_b32 s3, v255, 4
	v_readlane_b32 s8, v254, 2
	v_writelane_b32 v255, s2, 5
	v_mov_b32_e32 v0, s3
	ds_read_b32 v0, v0
	s_waitcnt lgkmcnt(0)
	v_readfirstlane_b32 s3, v0
	s_lshl_b32 s3, s3, 3
	s_add_i32 s97, s3, s8
	s_cmp_eq_u32 s8, 0
	s_cbranch_scc1 .Lstag_done
	s_mov_b32 s2, s8
.Lstag_loop:
	s_sleep 100
	s_sub_u32 s2, s2, 1
	s_cmp_lg_u32 s2, 0
	s_cbranch_scc1 .Lstag_loop
.Lstag_done:
	s_branch .LBB0_11
.LBB0_29:
	s_mov_b64 s[6:7], -1
